# U sub-pass 1 adds sub-pass 0 partial sums (8 partial-dot slices instead of 16); combine phase reads 8 slices
# speedup vs baseline: 1.1308x; 1.0021x over previous
; #define FP8_LO(w) __builtin_amdgcn_cvt_pk_f32_fp8((int)(w), false)
; #define FP8_HI(w) __builtin_amdgcn_cvt_pk_f32_fp8((int)(w), true)
; DI float dot16p(const u32x4 xa, const u32x4 xb, const u32x4 w) {
;     const f32x2 a0 = FP8_LO(w.x), a1 = FP8_HI(w.x), a2 = FP8_LO(w.y), a3 = FP8_HI(w.y), a4 = FP8_LO(w.z), a5 = FP8_HI(w.z), a6 = FP8_LO(w.w), a7 = FP8_HI(w.w);
;     return (bflo(xa.x) * a0.x + bfhi(xa.x) * a0.y + bflo(xa.y) * a1.x + bfhi(xa.y) * a1.y) + (bflo(xa.z) * a2.x + bfhi(xa.z) * a2.y + bflo(xa.w) * a3.x + bfhi(xa.w) * a3.y)
;          + (bflo(xb.x) * a4.x + bfhi(xb.x) * a4.y + bflo(xb.y) * a5.x + bfhi(xb.y) * a5.y) + (bflo(xb.z) * a6.x + bfhi(xb.z) * a6.y + bflo(xb.w) * a7.x + bfhi(xb.w) * a7.y);
; DI void gat_loadhu(const unsigned char* base, int idlo, int idhi, int g8, unsigned lo16, u32x4 (&buf)[8]) {
;     const int ids = g8 < 8 ? idlo : idhi, e0 = (g8 & 7) * 8;
; #pragma unroll
;     for (int j = 0; j < 8; ++j) buf[j] = *(const u32x4*)(base + ((unsigned)__shfl(ids, e0 + j) * (unsigned)D + lo16));
.Lpu_b0_nox:
	s_cmp_ge_u32 s0, 0x87
	s_cselect_b32 s19, 1, 0
	s_cmp_eq_u32 s47, 7
	s_cselect_b32 s19, s19, 0
	s_cmp_eq_u32 s19, 1
	s_cbranch_scc0 .Lpu_b0_nopd
	s_bfe_u32 s45, s0, 0x40003
	s_lshl_b32 s45, s45, 20
	s_add_u32 s45, s45, s8
	s_lshl_b32 s46, s9, 24
	s_add_u32 s45, s45, s46
	s_add_u32 s45, s45, 0x20000000
	s_add_u32 s22, s98, s45
	s_addc_u32 s23, s99, 0
	global_load_dwordx4 v[180:183], v2, s[22:23]
	global_load_dwordx4 v[192:195], v2, s[22:23] offset:128
	global_load_dwordx4 v[200:203], v2, s[22:23] offset:256
	global_load_dwordx4 v[244:247], v2, s[22:23] offset:384
.Lpu_b0_nopd:
	s_waitcnt lgkmcnt(0)
	s_add_u32 s44, s0, 2
	s_min_u32 s44, s44, 0xff
	s_bfe_u32 s45, s44, 0x10003
	s_lshl_b32 s45, s45, 12
	s_and_b32 s46, s44, 7
	s_lshl_b32 s46, s46, 6
	s_add_u32 s45, s45, s46
	v_add_u32_e32 v5, s45, v240
	ds_read_b128 v[72:75], v5
	ds_read_b128 v[76:79], v5 offset:16
	ds_read_b128 v[80:83], v5 offset:32
	ds_read_b128 v[84:87], v5 offset:48
	s_waitcnt vmcnt(15)
	v_cvt_pk_f32_fp8_e32 v[140:141], v8
	v_cvt_pk_f32_fp8_sdwa v[142:143], v8 src0_sel:WORD_1
	v_cvt_pk_f32_fp8_e32 v[144:145], v9
	v_cvt_pk_f32_fp8_sdwa v[146:147], v9 src0_sel:WORD_1
	v_pk_mul_f32 v[148:149], v[140:141], v[104:105]
	v_pk_fma_f32 v[148:149], v[142:143], v[106:107], v[148:149]
	v_pk_fma_f32 v[148:149], v[144:145], v[108:109], v[148:149]
	v_pk_fma_f32 v[148:149], v[146:147], v[110:111], v[148:149]
	v_cvt_pk_f32_fp8_e32 v[140:141], v10
	v_cvt_pk_f32_fp8_sdwa v[142:143], v10 src0_sel:WORD_1
	v_cvt_pk_f32_fp8_e32 v[144:145], v11
	v_cvt_pk_f32_fp8_sdwa v[146:147], v11 src0_sel:WORD_1
	v_pk_fma_f32 v[148:149], v[140:141], v[112:113], v[148:149]
	v_pk_fma_f32 v[148:149], v[142:143], v[114:115], v[148:149]
	v_pk_fma_f32 v[148:149], v[144:145], v[116:117], v[148:149]
	v_pk_fma_f32 v[148:149], v[146:147], v[118:119], v[148:149]
	v_add_f32_e32 v156, v148, v149
	v_lshl_add_u32 v3, v88, 7, v0
	global_load_dwordx4 v[8:11], v3, s[40:41]
	s_waitcnt vmcnt(15)
	v_cvt_pk_f32_fp8_e32 v[140:141], v12
	v_cvt_pk_f32_fp8_sdwa v[142:143], v12 src0_sel:WORD_1
	v_cvt_pk_f32_fp8_e32 v[144:145], v13
	v_cvt_pk_f32_fp8_sdwa v[146:147], v13 src0_sel:WORD_1
	v_pk_mul_f32 v[148:149], v[140:141], v[104:105]
	v_pk_fma_f32 v[148:149], v[142:143], v[106:107], v[148:149]
	v_pk_fma_f32 v[148:149], v[144:145], v[108:109], v[148:149]
	v_pk_fma_f32 v[148:149], v[146:147], v[110:111], v[148:149]
	v_cvt_pk_f32_fp8_e32 v[140:141], v14
	v_cvt_pk_f32_fp8_sdwa v[142:143], v14 src0_sel:WORD_1
	v_cvt_pk_f32_fp8_e32 v[144:145], v15
	v_cvt_pk_f32_fp8_sdwa v[146:147], v15 src0_sel:WORD_1
	v_pk_fma_f32 v[148:149], v[140:141], v[112:113], v[148:149]
	v_pk_fma_f32 v[148:149], v[142:143], v[114:115], v[148:149]
	v_pk_fma_f32 v[148:149], v[144:145], v[116:117], v[148:149]
	v_pk_fma_f32 v[148:149], v[146:147], v[118:119], v[148:149]
	v_add_f32_e32 v157, v148, v149
	v_lshl_add_u32 v4, v89, 7, v0
	global_load_dwordx4 v[12:15], v4, s[40:41]
	s_waitcnt vmcnt(15)
	v_cvt_pk_f32_fp8_e32 v[140:141], v16
	v_cvt_pk_f32_fp8_sdwa v[142:143], v16 src0_sel:WORD_1
	v_cvt_pk_f32_fp8_e32 v[144:145], v17
	v_cvt_pk_f32_fp8_sdwa v[146:147], v17 src0_sel:WORD_1
	v_pk_mul_f32 v[148:149], v[140:141], v[104:105]
	v_pk_fma_f32 v[148:149], v[142:143], v[106:107], v[148:149]
	v_pk_fma_f32 v[148:149], v[144:145], v[108:109], v[148:149]
	v_pk_fma_f32 v[148:149], v[146:147], v[110:111], v[148:149]
	v_cvt_pk_f32_fp8_e32 v[140:141], v18
	v_cvt_pk_f32_fp8_sdwa v[142:143], v18 src0_sel:WORD_1
	v_cvt_pk_f32_fp8_e32 v[144:145], v19
	v_cvt_pk_f32_fp8_sdwa v[146:147], v19 src0_sel:WORD_1
	v_pk_fma_f32 v[148:149], v[140:141], v[112:113], v[148:149]
	v_pk_fma_f32 v[148:149], v[142:143], v[114:115], v[148:149]
	v_pk_fma_f32 v[148:149], v[144:145], v[116:117], v[148:149]
	v_pk_fma_f32 v[148:149], v[146:147], v[118:119], v[148:149]
	v_add_f32_e32 v158, v148, v149
	v_lshl_add_u32 v3, v90, 7, v0
	global_load_dwordx4 v[16:19], v3, s[40:41]
	s_waitcnt vmcnt(15)
	v_cvt_pk_f32_fp8_e32 v[140:141], v20
	v_cvt_pk_f32_fp8_sdwa v[142:143], v20 src0_sel:WORD_1
	v_cvt_pk_f32_fp8_e32 v[144:145], v21
	v_cvt_pk_f32_fp8_sdwa v[146:147], v21 src0_sel:WORD_1
	v_pk_mul_f32 v[148:149], v[140:141], v[104:105]
	v_pk_fma_f32 v[148:149], v[142:143], v[106:107], v[148:149]
	v_pk_fma_f32 v[148:149], v[144:145], v[108:109], v[148:149]
	v_pk_fma_f32 v[148:149], v[146:147], v[110:111], v[148:149]
	v_cvt_pk_f32_fp8_e32 v[140:141], v22
	v_cvt_pk_f32_fp8_sdwa v[142:143], v22 src0_sel:WORD_1
	v_cvt_pk_f32_fp8_e32 v[144:145], v23
	v_cvt_pk_f32_fp8_sdwa v[146:147], v23 src0_sel:WORD_1
	v_pk_fma_f32 v[148:149], v[140:141], v[112:113], v[148:149]
	v_pk_fma_f32 v[148:149], v[142:143], v[114:115], v[148:149]
	v_pk_fma_f32 v[148:149], v[144:145], v[116:117], v[148:149]
	v_pk_fma_f32 v[148:149], v[146:147], v[118:119], v[148:149]
	v_add_f32_e32 v159, v148, v149
	v_lshl_add_u32 v4, v91, 7, v0
	global_load_dwordx4 v[20:23], v4, s[40:41]
	s_waitcnt vmcnt(15)
	v_cvt_pk_f32_fp8_e32 v[140:141], v24
	v_cvt_pk_f32_fp8_sdwa v[142:143], v24 src0_sel:WORD_1
	v_cvt_pk_f32_fp8_e32 v[144:145], v25
	v_cvt_pk_f32_fp8_sdwa v[146:147], v25 src0_sel:WORD_1
	v_pk_mul_f32 v[148:149], v[140:141], v[104:105]
	v_pk_fma_f32 v[148:149], v[142:143], v[106:107], v[148:149]
	v_pk_fma_f32 v[148:149], v[144:145], v[108:109], v[148:149]
	v_pk_fma_f32 v[148:149], v[146:147], v[110:111], v[148:149]
	v_cvt_pk_f32_fp8_e32 v[140:141], v26
	v_cvt_pk_f32_fp8_sdwa v[142:143], v26 src0_sel:WORD_1
	v_cvt_pk_f32_fp8_e32 v[144:145], v27
	v_cvt_pk_f32_fp8_sdwa v[146:147], v27 src0_sel:WORD_1
	v_pk_fma_f32 v[148:149], v[140:141], v[112:113], v[148:149]
	v_pk_fma_f32 v[148:149], v[142:143], v[114:115], v[148:149]
	v_pk_fma_f32 v[148:149], v[144:145], v[116:117], v[148:149]
	v_pk_fma_f32 v[148:149], v[146:147], v[118:119], v[148:149]
	v_add_f32_e32 v160, v148, v149
	v_lshl_add_u32 v3, v92, 7, v0
	global_load_dwordx4 v[24:27], v3, s[40:41]
	s_waitcnt vmcnt(15)
; #define FP8_LO(w) __builtin_amdgcn_cvt_pk_f32_fp8((int)(w), false)
; #define FP8_HI(w) __builtin_amdgcn_cvt_pk_f32_fp8((int)(w), true)
; DI float dot16p(const u32x4 xa, const u32x4 xb, const u32x4 w) {
;     const f32x2 a0 = FP8_LO(w.x), a1 = FP8_HI(w.x), a2 = FP8_LO(w.y), a3 = FP8_HI(w.y), a4 = FP8_LO(w.z), a5 = FP8_HI(w.z), a6 = FP8_LO(w.w), a7 = FP8_HI(w.w);
;     return (bflo(xa.x) * a0.x + bfhi(xa.x) * a0.y + bflo(xa.y) * a1.x + bfhi(xa.y) * a1.y) + (bflo(xa.z) * a2.x + bfhi(xa.z) * a2.y + bflo(xa.w) * a3.x + bfhi(xa.w) * a3.y)
;          + (bflo(xb.x) * a4.x + bfhi(xb.x) * a4.y + bflo(xb.y) * a5.x + bfhi(xb.y) * a5.y) + (bflo(xb.z) * a6.x + bfhi(xb.z) * a6.y + bflo(xb.w) * a7.x + bfhi(xb.w) * a7.y);
	v_cvt_pk_f32_fp8_e32 v[140:141], v28
	v_cvt_pk_f32_fp8_sdwa v[142:143], v28 src0_sel:WORD_1
	v_cvt_pk_f32_fp8_e32 v[144:145], v29
	v_cvt_pk_f32_fp8_sdwa v[146:147], v29 src0_sel:WORD_1
	v_pk_mul_f32 v[148:149], v[140:141], v[104:105]
	v_pk_fma_f32 v[148:149], v[142:143], v[106:107], v[148:149]
	v_pk_fma_f32 v[148:149], v[144:145], v[108:109], v[148:149]
	v_pk_fma_f32 v[148:149], v[146:147], v[110:111], v[148:149]
	v_cvt_pk_f32_fp8_e32 v[140:141], v30
	v_cvt_pk_f32_fp8_sdwa v[142:143], v30 src0_sel:WORD_1
	v_cvt_pk_f32_fp8_e32 v[144:145], v31
	v_cvt_pk_f32_fp8_sdwa v[146:147], v31 src0_sel:WORD_1
	v_pk_fma_f32 v[148:149], v[140:141], v[112:113], v[148:149]
	v_pk_fma_f32 v[148:149], v[142:143], v[114:115], v[148:149]
	v_pk_fma_f32 v[148:149], v[144:145], v[116:117], v[148:149]
	v_pk_fma_f32 v[148:149], v[146:147], v[118:119], v[148:149]
	v_add_f32_e32 v161, v148, v149
	v_lshl_add_u32 v4, v93, 7, v0
	global_load_dwordx4 v[28:31], v4, s[40:41]
	s_waitcnt vmcnt(15)
	v_cvt_pk_f32_fp8_e32 v[140:141], v32
	v_cvt_pk_f32_fp8_sdwa v[142:143], v32 src0_sel:WORD_1
	v_cvt_pk_f32_fp8_e32 v[144:145], v33
	v_cvt_pk_f32_fp8_sdwa v[146:147], v33 src0_sel:WORD_1
	v_pk_mul_f32 v[148:149], v[140:141], v[104:105]
	v_pk_fma_f32 v[148:149], v[142:143], v[106:107], v[148:149]
	v_pk_fma_f32 v[148:149], v[144:145], v[108:109], v[148:149]
	v_pk_fma_f32 v[148:149], v[146:147], v[110:111], v[148:149]
	v_cvt_pk_f32_fp8_e32 v[140:141], v34
	v_cvt_pk_f32_fp8_sdwa v[142:143], v34 src0_sel:WORD_1
	v_cvt_pk_f32_fp8_e32 v[144:145], v35
	v_cvt_pk_f32_fp8_sdwa v[146:147], v35 src0_sel:WORD_1
	v_pk_fma_f32 v[148:149], v[140:141], v[112:113], v[148:149]
	v_pk_fma_f32 v[148:149], v[142:143], v[114:115], v[148:149]
	v_pk_fma_f32 v[148:149], v[144:145], v[116:117], v[148:149]
	v_pk_fma_f32 v[148:149], v[146:147], v[118:119], v[148:149]
	v_add_f32_e32 v162, v148, v149
	v_lshl_add_u32 v3, v94, 7, v0
	global_load_dwordx4 v[32:35], v3, s[40:41]
	s_waitcnt vmcnt(15)
	v_cvt_pk_f32_fp8_e32 v[140:141], v36
	v_cvt_pk_f32_fp8_sdwa v[142:143], v36 src0_sel:WORD_1
	v_cvt_pk_f32_fp8_e32 v[144:145], v37
	v_cvt_pk_f32_fp8_sdwa v[146:147], v37 src0_sel:WORD_1
	v_pk_mul_f32 v[148:149], v[140:141], v[104:105]
	v_pk_fma_f32 v[148:149], v[142:143], v[106:107], v[148:149]
	v_pk_fma_f32 v[148:149], v[144:145], v[108:109], v[148:149]
	v_pk_fma_f32 v[148:149], v[146:147], v[110:111], v[148:149]
	v_cvt_pk_f32_fp8_e32 v[140:141], v38
	v_cvt_pk_f32_fp8_sdwa v[142:143], v38 src0_sel:WORD_1
	v_cvt_pk_f32_fp8_e32 v[144:145], v39
	v_cvt_pk_f32_fp8_sdwa v[146:147], v39 src0_sel:WORD_1
	v_pk_fma_f32 v[148:149], v[140:141], v[112:113], v[148:149]
	v_pk_fma_f32 v[148:149], v[142:143], v[114:115], v[148:149]
	v_pk_fma_f32 v[148:149], v[144:145], v[116:117], v[148:149]
	v_pk_fma_f32 v[148:149], v[146:147], v[118:119], v[148:149]
	v_add_f32_e32 v163, v148, v149
	v_lshl_add_u32 v4, v95, 7, v0
	global_load_dwordx4 v[36:39], v4, s[40:41]
	s_waitcnt vmcnt(15)
	v_cvt_pk_f32_fp8_e32 v[140:141], v40
	v_cvt_pk_f32_fp8_sdwa v[142:143], v40 src0_sel:WORD_1
	v_cvt_pk_f32_fp8_e32 v[144:145], v41
	v_cvt_pk_f32_fp8_sdwa v[146:147], v41 src0_sel:WORD_1
	v_pk_mul_f32 v[148:149], v[140:141], v[104:105]
	v_pk_fma_f32 v[148:149], v[142:143], v[106:107], v[148:149]
	v_pk_fma_f32 v[148:149], v[144:145], v[108:109], v[148:149]
	v_pk_fma_f32 v[148:149], v[146:147], v[110:111], v[148:149]
	v_cvt_pk_f32_fp8_e32 v[140:141], v42
	v_cvt_pk_f32_fp8_sdwa v[142:143], v42 src0_sel:WORD_1
	v_cvt_pk_f32_fp8_e32 v[144:145], v43
	v_cvt_pk_f32_fp8_sdwa v[146:147], v43 src0_sel:WORD_1
	v_pk_fma_f32 v[148:149], v[140:141], v[112:113], v[148:149]
	v_pk_fma_f32 v[148:149], v[142:143], v[114:115], v[148:149]
	v_pk_fma_f32 v[148:149], v[144:145], v[116:117], v[148:149]
	v_pk_fma_f32 v[148:149], v[146:147], v[118:119], v[148:149]
	v_add_f32_e32 v166, v148, v149
	v_lshl_add_u32 v3, v96, 7, v0
	global_load_dwordx4 v[40:43], v3, s[40:41]
	s_waitcnt vmcnt(15)
	v_cvt_pk_f32_fp8_e32 v[140:141], v44
	v_cvt_pk_f32_fp8_sdwa v[142:143], v44 src0_sel:WORD_1
	v_cvt_pk_f32_fp8_e32 v[144:145], v45
	v_cvt_pk_f32_fp8_sdwa v[146:147], v45 src0_sel:WORD_1
	v_pk_mul_f32 v[148:149], v[140:141], v[104:105]
	v_pk_fma_f32 v[148:149], v[142:143], v[106:107], v[148:149]
	v_pk_fma_f32 v[148:149], v[144:145], v[108:109], v[148:149]
	v_pk_fma_f32 v[148:149], v[146:147], v[110:111], v[148:149]
	v_cvt_pk_f32_fp8_e32 v[140:141], v46
	v_cvt_pk_f32_fp8_sdwa v[142:143], v46 src0_sel:WORD_1
	v_cvt_pk_f32_fp8_e32 v[144:145], v47
	v_cvt_pk_f32_fp8_sdwa v[146:147], v47 src0_sel:WORD_1
	v_pk_fma_f32 v[148:149], v[140:141], v[112:113], v[148:149]
	v_pk_fma_f32 v[148:149], v[142:143], v[114:115], v[148:149]
	v_pk_fma_f32 v[148:149], v[144:145], v[116:117], v[148:149]
	v_pk_fma_f32 v[148:149], v[146:147], v[118:119], v[148:149]
	v_add_f32_e32 v167, v148, v149
	v_lshl_add_u32 v4, v97, 7, v0
	global_load_dwordx4 v[44:47], v4, s[40:41]
	s_waitcnt vmcnt(15)
	v_cvt_pk_f32_fp8_e32 v[140:141], v48
	v_cvt_pk_f32_fp8_sdwa v[142:143], v48 src0_sel:WORD_1
	v_cvt_pk_f32_fp8_e32 v[144:145], v49
	v_cvt_pk_f32_fp8_sdwa v[146:147], v49 src0_sel:WORD_1
	v_pk_mul_f32 v[148:149], v[140:141], v[104:105]
	v_pk_fma_f32 v[148:149], v[142:143], v[106:107], v[148:149]
	v_pk_fma_f32 v[148:149], v[144:145], v[108:109], v[148:149]
	v_pk_fma_f32 v[148:149], v[146:147], v[110:111], v[148:149]
	v_cvt_pk_f32_fp8_e32 v[140:141], v50
	v_cvt_pk_f32_fp8_sdwa v[142:143], v50 src0_sel:WORD_1
	v_cvt_pk_f32_fp8_e32 v[144:145], v51
	v_cvt_pk_f32_fp8_sdwa v[146:147], v51 src0_sel:WORD_1
	v_pk_fma_f32 v[148:149], v[140:141], v[112:113], v[148:149]
	v_pk_fma_f32 v[148:149], v[142:143], v[114:115], v[148:149]
	v_pk_fma_f32 v[148:149], v[144:145], v[116:117], v[148:149]
	v_pk_fma_f32 v[148:149], v[146:147], v[118:119], v[148:149]
	v_add_f32_e32 v168, v148, v149
	v_lshl_add_u32 v3, v98, 7, v0
	global_load_dwordx4 v[48:51], v3, s[40:41]
	s_waitcnt vmcnt(15)
; #define FP8_LO(w) __builtin_amdgcn_cvt_pk_f32_fp8((int)(w), false)
; #define FP8_HI(w) __builtin_amdgcn_cvt_pk_f32_fp8((int)(w), true)
; DI float dot16p(const u32x4 xa, const u32x4 xb, const u32x4 w) {
;     const f32x2 a0 = FP8_LO(w.x), a1 = FP8_HI(w.x), a2 = FP8_LO(w.y), a3 = FP8_HI(w.y), a4 = FP8_LO(w.z), a5 = FP8_HI(w.z), a6 = FP8_LO(w.w), a7 = FP8_HI(w.w);
;     return (bflo(xa.x) * a0.x + bfhi(xa.x) * a0.y + bflo(xa.y) * a1.x + bfhi(xa.y) * a1.y) + (bflo(xa.z) * a2.x + bfhi(xa.z) * a2.y + bflo(xa.w) * a3.x + bfhi(xa.w) * a3.y)
;          + (bflo(xb.x) * a4.x + bfhi(xb.x) * a4.y + bflo(xb.y) * a5.x + bfhi(xb.y) * a5.y) + (bflo(xb.z) * a6.x + bfhi(xb.z) * a6.y + bflo(xb.w) * a7.x + bfhi(xb.w) * a7.y);
	v_cvt_pk_f32_fp8_e32 v[140:141], v52
	v_cvt_pk_f32_fp8_sdwa v[142:143], v52 src0_sel:WORD_1
	v_cvt_pk_f32_fp8_e32 v[144:145], v53
	v_cvt_pk_f32_fp8_sdwa v[146:147], v53 src0_sel:WORD_1
	v_pk_mul_f32 v[148:149], v[140:141], v[104:105]
	v_pk_fma_f32 v[148:149], v[142:143], v[106:107], v[148:149]
	v_pk_fma_f32 v[148:149], v[144:145], v[108:109], v[148:149]
	v_pk_fma_f32 v[148:149], v[146:147], v[110:111], v[148:149]
	v_cvt_pk_f32_fp8_e32 v[140:141], v54
	v_cvt_pk_f32_fp8_sdwa v[142:143], v54 src0_sel:WORD_1
	v_cvt_pk_f32_fp8_e32 v[144:145], v55
	v_cvt_pk_f32_fp8_sdwa v[146:147], v55 src0_sel:WORD_1
	v_pk_fma_f32 v[148:149], v[140:141], v[112:113], v[148:149]
	v_pk_fma_f32 v[148:149], v[142:143], v[114:115], v[148:149]
	v_pk_fma_f32 v[148:149], v[144:145], v[116:117], v[148:149]
	v_pk_fma_f32 v[148:149], v[146:147], v[118:119], v[148:149]
	v_add_f32_e32 v169, v148, v149
	v_lshl_add_u32 v4, v99, 7, v0
	global_load_dwordx4 v[52:55], v4, s[40:41]
	s_waitcnt vmcnt(15)
	v_cvt_pk_f32_fp8_e32 v[140:141], v56
	v_cvt_pk_f32_fp8_sdwa v[142:143], v56 src0_sel:WORD_1
	v_cvt_pk_f32_fp8_e32 v[144:145], v57
	v_cvt_pk_f32_fp8_sdwa v[146:147], v57 src0_sel:WORD_1
	v_pk_mul_f32 v[148:149], v[140:141], v[104:105]
	v_pk_fma_f32 v[148:149], v[142:143], v[106:107], v[148:149]
	v_pk_fma_f32 v[148:149], v[144:145], v[108:109], v[148:149]
	v_pk_fma_f32 v[148:149], v[146:147], v[110:111], v[148:149]
	v_cvt_pk_f32_fp8_e32 v[140:141], v58
	v_cvt_pk_f32_fp8_sdwa v[142:143], v58 src0_sel:WORD_1
	v_cvt_pk_f32_fp8_e32 v[144:145], v59
	v_cvt_pk_f32_fp8_sdwa v[146:147], v59 src0_sel:WORD_1
	v_pk_fma_f32 v[148:149], v[140:141], v[112:113], v[148:149]
	v_pk_fma_f32 v[148:149], v[142:143], v[114:115], v[148:149]
	v_pk_fma_f32 v[148:149], v[144:145], v[116:117], v[148:149]
	v_pk_fma_f32 v[148:149], v[146:147], v[118:119], v[148:149]
	v_add_f32_e32 v170, v148, v149
	v_lshl_add_u32 v3, v100, 7, v0
	global_load_dwordx4 v[56:59], v3, s[40:41]
	s_waitcnt vmcnt(15)
	v_cvt_pk_f32_fp8_e32 v[140:141], v60
	v_cvt_pk_f32_fp8_sdwa v[142:143], v60 src0_sel:WORD_1
	v_cvt_pk_f32_fp8_e32 v[144:145], v61
	v_cvt_pk_f32_fp8_sdwa v[146:147], v61 src0_sel:WORD_1
	v_pk_mul_f32 v[148:149], v[140:141], v[104:105]
	v_pk_fma_f32 v[148:149], v[142:143], v[106:107], v[148:149]
	v_pk_fma_f32 v[148:149], v[144:145], v[108:109], v[148:149]
	v_pk_fma_f32 v[148:149], v[146:147], v[110:111], v[148:149]
	v_cvt_pk_f32_fp8_e32 v[140:141], v62
	v_cvt_pk_f32_fp8_sdwa v[142:143], v62 src0_sel:WORD_1
	v_cvt_pk_f32_fp8_e32 v[144:145], v63
	v_cvt_pk_f32_fp8_sdwa v[146:147], v63 src0_sel:WORD_1
	v_pk_fma_f32 v[148:149], v[140:141], v[112:113], v[148:149]
	v_pk_fma_f32 v[148:149], v[142:143], v[114:115], v[148:149]
	v_pk_fma_f32 v[148:149], v[144:145], v[116:117], v[148:149]
	v_pk_fma_f32 v[148:149], v[146:147], v[118:119], v[148:149]
	v_add_f32_e32 v171, v148, v149
	v_lshl_add_u32 v4, v101, 7, v0
	global_load_dwordx4 v[60:63], v4, s[40:41]
	s_waitcnt vmcnt(15)
	v_cvt_pk_f32_fp8_e32 v[140:141], v64
	v_cvt_pk_f32_fp8_sdwa v[142:143], v64 src0_sel:WORD_1
	v_cvt_pk_f32_fp8_e32 v[144:145], v65
	v_cvt_pk_f32_fp8_sdwa v[146:147], v65 src0_sel:WORD_1
	v_pk_mul_f32 v[148:149], v[140:141], v[104:105]
	v_pk_fma_f32 v[148:149], v[142:143], v[106:107], v[148:149]
	v_pk_fma_f32 v[148:149], v[144:145], v[108:109], v[148:149]
	v_pk_fma_f32 v[148:149], v[146:147], v[110:111], v[148:149]
	v_cvt_pk_f32_fp8_e32 v[140:141], v66
	v_cvt_pk_f32_fp8_sdwa v[142:143], v66 src0_sel:WORD_1
	v_cvt_pk_f32_fp8_e32 v[144:145], v67
	v_cvt_pk_f32_fp8_sdwa v[146:147], v67 src0_sel:WORD_1
	v_pk_fma_f32 v[148:149], v[140:141], v[112:113], v[148:149]
	v_pk_fma_f32 v[148:149], v[142:143], v[114:115], v[148:149]
	v_pk_fma_f32 v[148:149], v[144:145], v[116:117], v[148:149]
	v_pk_fma_f32 v[148:149], v[146:147], v[118:119], v[148:149]
	v_add_f32_e32 v172, v148, v149
	v_lshl_add_u32 v3, v102, 7, v0
	global_load_dwordx4 v[64:67], v3, s[40:41]
	s_waitcnt vmcnt(15)
; DI float dots4h(const u32x4 xa, const u32x4 xb, const u32x4 b0, const u32x4 b1, const u32x4 b2, const u32x4 b3, int lane) {
;     const float d0 = dot16p(xa, xb, b0), d1 = dot16p(xa, xb, b1); __builtin_amdgcn_sched_barrier(0);
;     const float d2 = dot16p(xa, xb, b2), d3 = dot16p(xa, xb, b3); __builtin_amdgcn_sched_barrier(0);
;     const bool p1 = lane & 1, p2 = lane & 2;
;     const float b0s = (p1 ? d1 : d0) + __shfl_xor(p1 ? d0 : d1, 1);
;     const float b1s = (p1 ? d3 : d2) + __shfl_xor(p1 ? d2 : d3, 1);
;     float cs = (p2 ? b1s : b0s) + __shfl_xor(p2 ? b0s : b1s, 2);
;     cs += __shfl_xor(cs, 4); cs += __shfl_xor(cs, 8); cs += __shfl_xor(cs, 16); cs += __shfl_xor(cs, 32);
;     return cs;
; DI void phase_peer_u(const Args& a, int layer, int ci) {
;     ...
;             if (ci == 0) { PD[(size_t)m * 128 + lane] = rA; PD[(size_t)m * 128 + 64 + lane] = rB; }
	v_cvt_pk_f32_fp8_e32 v[140:141], v68
	v_cvt_pk_f32_fp8_sdwa v[142:143], v68 src0_sel:WORD_1
	v_cvt_pk_f32_fp8_e32 v[144:145], v69
	v_cvt_pk_f32_fp8_sdwa v[146:147], v69 src0_sel:WORD_1
	v_pk_mul_f32 v[148:149], v[140:141], v[104:105]
	v_pk_fma_f32 v[148:149], v[142:143], v[106:107], v[148:149]
	v_pk_fma_f32 v[148:149], v[144:145], v[108:109], v[148:149]
	v_pk_fma_f32 v[148:149], v[146:147], v[110:111], v[148:149]
	v_cvt_pk_f32_fp8_e32 v[140:141], v70
	v_cvt_pk_f32_fp8_sdwa v[142:143], v70 src0_sel:WORD_1
	v_cvt_pk_f32_fp8_e32 v[144:145], v71
	v_cvt_pk_f32_fp8_sdwa v[146:147], v71 src0_sel:WORD_1
	v_pk_fma_f32 v[148:149], v[140:141], v[112:113], v[148:149]
	v_pk_fma_f32 v[148:149], v[142:143], v[114:115], v[148:149]
	v_pk_fma_f32 v[148:149], v[144:145], v[116:117], v[148:149]
	v_pk_fma_f32 v[148:149], v[146:147], v[118:119], v[148:149]
	v_add_f32_e32 v173, v148, v149
	v_lshl_add_u32 v4, v103, 7, v0
	global_load_dwordx4 v[68:71], v4, s[40:41]
	v_cndmask_b32_e64 v152, v156, v157, s[34:35]
	v_cndmask_b32_e64 v174, v157, v156, s[34:35]
	v_cndmask_b32_e64 v153, v158, v159, s[34:35]
	v_cndmask_b32_e64 v175, v159, v158, s[34:35]
	v_cndmask_b32_e64 v154, v160, v161, s[34:35]
	v_cndmask_b32_e64 v176, v161, v160, s[34:35]
	v_cndmask_b32_e64 v155, v162, v163, s[34:35]
	v_cndmask_b32_e64 v177, v163, v162, s[34:35]
	v_add_f32_dpp v156, v174, v152 quad_perm:[1,0,3,2] row_mask:0xf bank_mask:0xf
	v_add_f32_dpp v157, v175, v153 quad_perm:[1,0,3,2] row_mask:0xf bank_mask:0xf
	v_add_f32_dpp v158, v176, v154 quad_perm:[1,0,3,2] row_mask:0xf bank_mask:0xf
	v_add_f32_dpp v159, v177, v155 quad_perm:[1,0,3,2] row_mask:0xf bank_mask:0xf
	v_cndmask_b32_e64 v152, v166, v167, s[34:35]
	v_cndmask_b32_e64 v174, v167, v166, s[34:35]
	v_cndmask_b32_e64 v153, v168, v169, s[34:35]
	v_cndmask_b32_e64 v175, v169, v168, s[34:35]
	v_cndmask_b32_e64 v154, v170, v171, s[34:35]
	v_cndmask_b32_e64 v176, v171, v170, s[34:35]
	v_cndmask_b32_e64 v155, v172, v173, s[34:35]
	v_cndmask_b32_e64 v177, v173, v172, s[34:35]
	v_add_f32_dpp v160, v174, v152 quad_perm:[1,0,3,2] row_mask:0xf bank_mask:0xf
	v_add_f32_dpp v161, v175, v153 quad_perm:[1,0,3,2] row_mask:0xf bank_mask:0xf
	v_add_f32_dpp v162, v176, v154 quad_perm:[1,0,3,2] row_mask:0xf bank_mask:0xf
	v_add_f32_dpp v163, v177, v155 quad_perm:[1,0,3,2] row_mask:0xf bank_mask:0xf
	v_cndmask_b32_e64 v152, v156, v157, s[48:49]
	v_cndmask_b32_e64 v174, v157, v156, s[48:49]
	v_cndmask_b32_e64 v153, v158, v159, s[48:49]
	v_cndmask_b32_e64 v175, v159, v158, s[48:49]
	v_cndmask_b32_e64 v154, v160, v161, s[48:49]
	v_cndmask_b32_e64 v176, v161, v160, s[48:49]
	v_cndmask_b32_e64 v155, v162, v163, s[48:49]
	v_cndmask_b32_e64 v177, v163, v162, s[48:49]
	v_add_f32_dpp v156, v174, v152 quad_perm:[2,3,0,1] row_mask:0xf bank_mask:0xf
	v_add_f32_dpp v157, v175, v153 quad_perm:[2,3,0,1] row_mask:0xf bank_mask:0xf
	v_add_f32_dpp v158, v176, v154 quad_perm:[2,3,0,1] row_mask:0xf bank_mask:0xf
	v_add_f32_dpp v159, v177, v155 quad_perm:[2,3,0,1] row_mask:0xf bank_mask:0xf
	v_mov_b64_e32 v[216:217], v[218:219]
	v_mov_b64_e32 v[218:219], v[220:221]
	v_mov_b64_e32 v[220:221], v[222:223]
	v_mov_b64_e32 v[222:223], v[224:225]
	v_mov_b64_e32 v[224:225], v[226:227]
	v_mov_b64_e32 v[226:227], v[232:233]
	v_mov_b64_e32 v[232:233], v[234:235]
	v_cndmask_b32_e64 v152, v156, v157, s[50:51]
	v_cndmask_b32_e64 v174, v157, v156, s[50:51]
	v_cndmask_b32_e64 v153, v158, v159, s[50:51]
	v_cndmask_b32_e64 v175, v159, v158, s[50:51]
	v_add_f32_dpp v234, v174, v152 row_shl:4 row_mask:0xf bank_mask:0x5
	v_add_f32_dpp v234, v174, v152 row_shr:4 row_mask:0xf bank_mask:0xa
	v_add_f32_dpp v235, v175, v153 row_shl:4 row_mask:0xf bank_mask:0x5
	v_add_f32_dpp v235, v175, v153 row_shr:4 row_mask:0xf bank_mask:0xa
	s_cmp_eq_u32 s47, 7
	s_cbranch_scc0 .Lpu_b0_nost
	s_bfe_u32 s45, s0, 0x40003
	s_lshl_b32 s45, s45, 20
	s_add_u32 s45, s45, s8
	s_lshr_b32 s46, s0, 7
	s_add_u32 s46, s46, s9
	s_lshl_b32 s46, s46, 24
	s_add_u32 s45, s45, s46
	s_add_u32 s45, s45, 0x20000000
	s_add_u32 s42, s98, s45
	s_addc_u32 s43, s99, 0
	s_cmp_ge_u32 s0, 0x80
	s_cbranch_scc0 .Lpu_b0_noadd
	v_pk_add_f32 v[216:217], v[216:217], v[180:181]
	v_pk_add_f32 v[218:219], v[218:219], v[182:183]
	v_pk_add_f32 v[220:221], v[220:221], v[192:193]
	v_pk_add_f32 v[222:223], v[222:223], v[194:195]
	v_pk_add_f32 v[224:225], v[224:225], v[200:201]
	v_pk_add_f32 v[226:227], v[226:227], v[202:203]
	v_pk_add_f32 v[232:233], v[232:233], v[244:245]
	v_pk_add_f32 v[234:235], v[234:235], v[246:247]
.Lpu_b0_noadd:
	global_store_dwordx4 v2, v[216:219], s[42:43]
	global_store_dwordx4 v2, v[220:223], s[42:43] offset:128
	global_store_dwordx4 v2, v[224:227], s[42:43] offset:256
	global_store_dwordx4 v2, v[232:235], s[42:43] offset:384
	v_lshlrev_b32_e32 v104, 16, v120
	v_and_b32_e32 v105, 0xffff0000, v120
	v_lshlrev_b32_e32 v106, 16, v121
	v_and_b32_e32 v107, 0xffff0000, v121
	v_lshlrev_b32_e32 v108, 16, v122
	v_and_b32_e32 v109, 0xffff0000, v122
	v_lshlrev_b32_e32 v110, 16, v123
	v_and_b32_e32 v111, 0xffff0000, v123
	v_lshlrev_b32_e32 v112, 16, v124
	v_and_b32_e32 v113, 0xffff0000, v124
	v_lshlrev_b32_e32 v114, 16, v125
	v_and_b32_e32 v115, 0xffff0000, v125
	v_lshlrev_b32_e32 v116, 16, v126
	v_and_b32_e32 v117, 0xffff0000, v126
	v_lshlrev_b32_e32 v118, 16, v127
	v_and_b32_e32 v119, 0xffff0000, v127

; #define FP8_LO(w) __builtin_amdgcn_cvt_pk_f32_fp8((int)(w), false)
; #define FP8_HI(w) __builtin_amdgcn_cvt_pk_f32_fp8((int)(w), true)
; DI float dot16p(const u32x4 xa, const u32x4 xb, const u32x4 w) {
;     const f32x2 a0 = FP8_LO(w.x), a1 = FP8_HI(w.x), a2 = FP8_LO(w.y), a3 = FP8_HI(w.y), a4 = FP8_LO(w.z), a5 = FP8_HI(w.z), a6 = FP8_LO(w.w), a7 = FP8_HI(w.w);
;     return (bflo(xa.x) * a0.x + bfhi(xa.x) * a0.y + bflo(xa.y) * a1.x + bfhi(xa.y) * a1.y) + (bflo(xa.z) * a2.x + bfhi(xa.z) * a2.y + bflo(xa.w) * a3.x + bfhi(xa.w) * a3.y)
;          + (bflo(xb.x) * a4.x + bfhi(xb.x) * a4.y + bflo(xb.y) * a5.x + bfhi(xb.y) * a5.y) + (bflo(xb.z) * a6.x + bfhi(xb.z) * a6.y + bflo(xb.w) * a7.x + bfhi(xb.w) * a7.y);
; DI void gat_loadhu(const unsigned char* base, int idlo, int idhi, int g8, unsigned lo16, u32x4 (&buf)[8]) {
;     const int ids = g8 < 8 ? idlo : idhi, e0 = (g8 & 7) * 8;
; #pragma unroll
;     for (int j = 0; j < 8; ++j) buf[j] = *(const u32x4*)(base + ((unsigned)__shfl(ids, e0 + j) * (unsigned)D + lo16));
.Lpu_b1_nopd:
	s_waitcnt lgkmcnt(0)
	s_add_u32 s44, s0, 2
	s_min_u32 s44, s44, 0xff
	s_bfe_u32 s45, s44, 0x10003
	s_lshl_b32 s45, s45, 12
	s_and_b32 s46, s44, 7
	s_lshl_b32 s46, s46, 6
	s_add_u32 s45, s45, s46
	v_add_u32_e32 v5, s45, v240
	ds_read_b128 v[88:91], v5
	ds_read_b128 v[92:95], v5 offset:16
	ds_read_b128 v[96:99], v5 offset:32
	ds_read_b128 v[100:103], v5 offset:48
	s_waitcnt vmcnt(15)
	v_cvt_pk_f32_fp8_e32 v[140:141], v8
	v_cvt_pk_f32_fp8_sdwa v[142:143], v8 src0_sel:WORD_1
	v_cvt_pk_f32_fp8_e32 v[144:145], v9
	v_cvt_pk_f32_fp8_sdwa v[146:147], v9 src0_sel:WORD_1
	v_pk_mul_f32 v[148:149], v[140:141], v[104:105]
	v_pk_fma_f32 v[148:149], v[142:143], v[106:107], v[148:149]
	v_pk_fma_f32 v[148:149], v[144:145], v[108:109], v[148:149]
	v_pk_fma_f32 v[148:149], v[146:147], v[110:111], v[148:149]
	v_cvt_pk_f32_fp8_e32 v[140:141], v10
	v_cvt_pk_f32_fp8_sdwa v[142:143], v10 src0_sel:WORD_1
	v_cvt_pk_f32_fp8_e32 v[144:145], v11
	v_cvt_pk_f32_fp8_sdwa v[146:147], v11 src0_sel:WORD_1
	v_pk_fma_f32 v[148:149], v[140:141], v[112:113], v[148:149]
	v_pk_fma_f32 v[148:149], v[142:143], v[114:115], v[148:149]
	v_pk_fma_f32 v[148:149], v[144:145], v[116:117], v[148:149]
	v_pk_fma_f32 v[148:149], v[146:147], v[118:119], v[148:149]
	v_add_f32_e32 v156, v148, v149
	v_lshl_add_u32 v3, v72, 7, v0
	global_load_dwordx4 v[8:11], v3, s[40:41]
	s_waitcnt vmcnt(15)
	v_cvt_pk_f32_fp8_e32 v[140:141], v12
	v_cvt_pk_f32_fp8_sdwa v[142:143], v12 src0_sel:WORD_1
	v_cvt_pk_f32_fp8_e32 v[144:145], v13
	v_cvt_pk_f32_fp8_sdwa v[146:147], v13 src0_sel:WORD_1
	v_pk_mul_f32 v[148:149], v[140:141], v[104:105]
	v_pk_fma_f32 v[148:149], v[142:143], v[106:107], v[148:149]
	v_pk_fma_f32 v[148:149], v[144:145], v[108:109], v[148:149]
	v_pk_fma_f32 v[148:149], v[146:147], v[110:111], v[148:149]
	v_cvt_pk_f32_fp8_e32 v[140:141], v14
	v_cvt_pk_f32_fp8_sdwa v[142:143], v14 src0_sel:WORD_1
	v_cvt_pk_f32_fp8_e32 v[144:145], v15
	v_cvt_pk_f32_fp8_sdwa v[146:147], v15 src0_sel:WORD_1
	v_pk_fma_f32 v[148:149], v[140:141], v[112:113], v[148:149]
	v_pk_fma_f32 v[148:149], v[142:143], v[114:115], v[148:149]
	v_pk_fma_f32 v[148:149], v[144:145], v[116:117], v[148:149]
	v_pk_fma_f32 v[148:149], v[146:147], v[118:119], v[148:149]
	v_add_f32_e32 v157, v148, v149
	v_lshl_add_u32 v4, v73, 7, v0
	global_load_dwordx4 v[12:15], v4, s[40:41]
	s_waitcnt vmcnt(15)
	v_cvt_pk_f32_fp8_e32 v[140:141], v16
	v_cvt_pk_f32_fp8_sdwa v[142:143], v16 src0_sel:WORD_1
	v_cvt_pk_f32_fp8_e32 v[144:145], v17
	v_cvt_pk_f32_fp8_sdwa v[146:147], v17 src0_sel:WORD_1
	v_pk_mul_f32 v[148:149], v[140:141], v[104:105]
	v_pk_fma_f32 v[148:149], v[142:143], v[106:107], v[148:149]
	v_pk_fma_f32 v[148:149], v[144:145], v[108:109], v[148:149]
	v_pk_fma_f32 v[148:149], v[146:147], v[110:111], v[148:149]
	v_cvt_pk_f32_fp8_e32 v[140:141], v18
	v_cvt_pk_f32_fp8_sdwa v[142:143], v18 src0_sel:WORD_1
	v_cvt_pk_f32_fp8_e32 v[144:145], v19
	v_cvt_pk_f32_fp8_sdwa v[146:147], v19 src0_sel:WORD_1
	v_pk_fma_f32 v[148:149], v[140:141], v[112:113], v[148:149]
	v_pk_fma_f32 v[148:149], v[142:143], v[114:115], v[148:149]
	v_pk_fma_f32 v[148:149], v[144:145], v[116:117], v[148:149]
	v_pk_fma_f32 v[148:149], v[146:147], v[118:119], v[148:149]
	v_add_f32_e32 v158, v148, v149
	v_lshl_add_u32 v3, v74, 7, v0
	global_load_dwordx4 v[16:19], v3, s[40:41]
	s_waitcnt vmcnt(15)
	v_cvt_pk_f32_fp8_e32 v[140:141], v20
	v_cvt_pk_f32_fp8_sdwa v[142:143], v20 src0_sel:WORD_1
	v_cvt_pk_f32_fp8_e32 v[144:145], v21
	v_cvt_pk_f32_fp8_sdwa v[146:147], v21 src0_sel:WORD_1
	v_pk_mul_f32 v[148:149], v[140:141], v[104:105]
	v_pk_fma_f32 v[148:149], v[142:143], v[106:107], v[148:149]
	v_pk_fma_f32 v[148:149], v[144:145], v[108:109], v[148:149]
	v_pk_fma_f32 v[148:149], v[146:147], v[110:111], v[148:149]
	v_cvt_pk_f32_fp8_e32 v[140:141], v22
	v_cvt_pk_f32_fp8_sdwa v[142:143], v22 src0_sel:WORD_1
	v_cvt_pk_f32_fp8_e32 v[144:145], v23
	v_cvt_pk_f32_fp8_sdwa v[146:147], v23 src0_sel:WORD_1
	v_pk_fma_f32 v[148:149], v[140:141], v[112:113], v[148:149]
	v_pk_fma_f32 v[148:149], v[142:143], v[114:115], v[148:149]
	v_pk_fma_f32 v[148:149], v[144:145], v[116:117], v[148:149]
	v_pk_fma_f32 v[148:149], v[146:147], v[118:119], v[148:149]
	v_add_f32_e32 v159, v148, v149
	v_lshl_add_u32 v4, v75, 7, v0
	global_load_dwordx4 v[20:23], v4, s[40:41]
	s_waitcnt vmcnt(15)
	v_cvt_pk_f32_fp8_e32 v[140:141], v24
	v_cvt_pk_f32_fp8_sdwa v[142:143], v24 src0_sel:WORD_1
	v_cvt_pk_f32_fp8_e32 v[144:145], v25
	v_cvt_pk_f32_fp8_sdwa v[146:147], v25 src0_sel:WORD_1
	v_pk_mul_f32 v[148:149], v[140:141], v[104:105]
	v_pk_fma_f32 v[148:149], v[142:143], v[106:107], v[148:149]
	v_pk_fma_f32 v[148:149], v[144:145], v[108:109], v[148:149]
	v_pk_fma_f32 v[148:149], v[146:147], v[110:111], v[148:149]
	v_cvt_pk_f32_fp8_e32 v[140:141], v26
	v_cvt_pk_f32_fp8_sdwa v[142:143], v26 src0_sel:WORD_1
	v_cvt_pk_f32_fp8_e32 v[144:145], v27
	v_cvt_pk_f32_fp8_sdwa v[146:147], v27 src0_sel:WORD_1
	v_pk_fma_f32 v[148:149], v[140:141], v[112:113], v[148:149]
	v_pk_fma_f32 v[148:149], v[142:143], v[114:115], v[148:149]
	v_pk_fma_f32 v[148:149], v[144:145], v[116:117], v[148:149]
	v_pk_fma_f32 v[148:149], v[146:147], v[118:119], v[148:149]
	v_add_f32_e32 v160, v148, v149
	v_lshl_add_u32 v3, v76, 7, v0
	global_load_dwordx4 v[24:27], v3, s[40:41]
	s_waitcnt vmcnt(15)
; #define FP8_LO(w) __builtin_amdgcn_cvt_pk_f32_fp8((int)(w), false)
; #define FP8_HI(w) __builtin_amdgcn_cvt_pk_f32_fp8((int)(w), true)
; DI float dot16p(const u32x4 xa, const u32x4 xb, const u32x4 w) {
;     const f32x2 a0 = FP8_LO(w.x), a1 = FP8_HI(w.x), a2 = FP8_LO(w.y), a3 = FP8_HI(w.y), a4 = FP8_LO(w.z), a5 = FP8_HI(w.z), a6 = FP8_LO(w.w), a7 = FP8_HI(w.w);
;     return (bflo(xa.x) * a0.x + bfhi(xa.x) * a0.y + bflo(xa.y) * a1.x + bfhi(xa.y) * a1.y) + (bflo(xa.z) * a2.x + bfhi(xa.z) * a2.y + bflo(xa.w) * a3.x + bfhi(xa.w) * a3.y)
;          + (bflo(xb.x) * a4.x + bfhi(xb.x) * a4.y + bflo(xb.y) * a5.x + bfhi(xb.y) * a5.y) + (bflo(xb.z) * a6.x + bfhi(xb.z) * a6.y + bflo(xb.w) * a7.x + bfhi(xb.w) * a7.y);
	v_cvt_pk_f32_fp8_e32 v[140:141], v28
	v_cvt_pk_f32_fp8_sdwa v[142:143], v28 src0_sel:WORD_1
	v_cvt_pk_f32_fp8_e32 v[144:145], v29
	v_cvt_pk_f32_fp8_sdwa v[146:147], v29 src0_sel:WORD_1
	v_pk_mul_f32 v[148:149], v[140:141], v[104:105]
	v_pk_fma_f32 v[148:149], v[142:143], v[106:107], v[148:149]
	v_pk_fma_f32 v[148:149], v[144:145], v[108:109], v[148:149]
	v_pk_fma_f32 v[148:149], v[146:147], v[110:111], v[148:149]
	v_cvt_pk_f32_fp8_e32 v[140:141], v30
	v_cvt_pk_f32_fp8_sdwa v[142:143], v30 src0_sel:WORD_1
	v_cvt_pk_f32_fp8_e32 v[144:145], v31
	v_cvt_pk_f32_fp8_sdwa v[146:147], v31 src0_sel:WORD_1
	v_pk_fma_f32 v[148:149], v[140:141], v[112:113], v[148:149]
	v_pk_fma_f32 v[148:149], v[142:143], v[114:115], v[148:149]
	v_pk_fma_f32 v[148:149], v[144:145], v[116:117], v[148:149]
	v_pk_fma_f32 v[148:149], v[146:147], v[118:119], v[148:149]
	v_add_f32_e32 v161, v148, v149
	v_lshl_add_u32 v4, v77, 7, v0
	global_load_dwordx4 v[28:31], v4, s[40:41]
	s_waitcnt vmcnt(15)
	v_cvt_pk_f32_fp8_e32 v[140:141], v32
	v_cvt_pk_f32_fp8_sdwa v[142:143], v32 src0_sel:WORD_1
	v_cvt_pk_f32_fp8_e32 v[144:145], v33
	v_cvt_pk_f32_fp8_sdwa v[146:147], v33 src0_sel:WORD_1
	v_pk_mul_f32 v[148:149], v[140:141], v[104:105]
	v_pk_fma_f32 v[148:149], v[142:143], v[106:107], v[148:149]
	v_pk_fma_f32 v[148:149], v[144:145], v[108:109], v[148:149]
	v_pk_fma_f32 v[148:149], v[146:147], v[110:111], v[148:149]
	v_cvt_pk_f32_fp8_e32 v[140:141], v34
	v_cvt_pk_f32_fp8_sdwa v[142:143], v34 src0_sel:WORD_1
	v_cvt_pk_f32_fp8_e32 v[144:145], v35
	v_cvt_pk_f32_fp8_sdwa v[146:147], v35 src0_sel:WORD_1
	v_pk_fma_f32 v[148:149], v[140:141], v[112:113], v[148:149]
	v_pk_fma_f32 v[148:149], v[142:143], v[114:115], v[148:149]
	v_pk_fma_f32 v[148:149], v[144:145], v[116:117], v[148:149]
	v_pk_fma_f32 v[148:149], v[146:147], v[118:119], v[148:149]
	v_add_f32_e32 v162, v148, v149
	v_lshl_add_u32 v3, v78, 7, v0
	global_load_dwordx4 v[32:35], v3, s[40:41]
	s_waitcnt vmcnt(15)
	v_cvt_pk_f32_fp8_e32 v[140:141], v36
	v_cvt_pk_f32_fp8_sdwa v[142:143], v36 src0_sel:WORD_1
	v_cvt_pk_f32_fp8_e32 v[144:145], v37
	v_cvt_pk_f32_fp8_sdwa v[146:147], v37 src0_sel:WORD_1
	v_pk_mul_f32 v[148:149], v[140:141], v[104:105]
	v_pk_fma_f32 v[148:149], v[142:143], v[106:107], v[148:149]
	v_pk_fma_f32 v[148:149], v[144:145], v[108:109], v[148:149]
	v_pk_fma_f32 v[148:149], v[146:147], v[110:111], v[148:149]
	v_cvt_pk_f32_fp8_e32 v[140:141], v38
	v_cvt_pk_f32_fp8_sdwa v[142:143], v38 src0_sel:WORD_1
	v_cvt_pk_f32_fp8_e32 v[144:145], v39
	v_cvt_pk_f32_fp8_sdwa v[146:147], v39 src0_sel:WORD_1
	v_pk_fma_f32 v[148:149], v[140:141], v[112:113], v[148:149]
	v_pk_fma_f32 v[148:149], v[142:143], v[114:115], v[148:149]
	v_pk_fma_f32 v[148:149], v[144:145], v[116:117], v[148:149]
	v_pk_fma_f32 v[148:149], v[146:147], v[118:119], v[148:149]
	v_add_f32_e32 v163, v148, v149
	v_lshl_add_u32 v4, v79, 7, v0
	global_load_dwordx4 v[36:39], v4, s[40:41]
	s_waitcnt vmcnt(15)
	v_cvt_pk_f32_fp8_e32 v[140:141], v40
	v_cvt_pk_f32_fp8_sdwa v[142:143], v40 src0_sel:WORD_1
	v_cvt_pk_f32_fp8_e32 v[144:145], v41
	v_cvt_pk_f32_fp8_sdwa v[146:147], v41 src0_sel:WORD_1
	v_pk_mul_f32 v[148:149], v[140:141], v[104:105]
	v_pk_fma_f32 v[148:149], v[142:143], v[106:107], v[148:149]
	v_pk_fma_f32 v[148:149], v[144:145], v[108:109], v[148:149]
	v_pk_fma_f32 v[148:149], v[146:147], v[110:111], v[148:149]
	v_cvt_pk_f32_fp8_e32 v[140:141], v42
	v_cvt_pk_f32_fp8_sdwa v[142:143], v42 src0_sel:WORD_1
	v_cvt_pk_f32_fp8_e32 v[144:145], v43
	v_cvt_pk_f32_fp8_sdwa v[146:147], v43 src0_sel:WORD_1
	v_pk_fma_f32 v[148:149], v[140:141], v[112:113], v[148:149]
	v_pk_fma_f32 v[148:149], v[142:143], v[114:115], v[148:149]
	v_pk_fma_f32 v[148:149], v[144:145], v[116:117], v[148:149]
	v_pk_fma_f32 v[148:149], v[146:147], v[118:119], v[148:149]
	v_add_f32_e32 v166, v148, v149
	v_lshl_add_u32 v3, v80, 7, v0
	global_load_dwordx4 v[40:43], v3, s[40:41]
	s_waitcnt vmcnt(15)
	v_cvt_pk_f32_fp8_e32 v[140:141], v44
	v_cvt_pk_f32_fp8_sdwa v[142:143], v44 src0_sel:WORD_1
	v_cvt_pk_f32_fp8_e32 v[144:145], v45
	v_cvt_pk_f32_fp8_sdwa v[146:147], v45 src0_sel:WORD_1
	v_pk_mul_f32 v[148:149], v[140:141], v[104:105]
	v_pk_fma_f32 v[148:149], v[142:143], v[106:107], v[148:149]
	v_pk_fma_f32 v[148:149], v[144:145], v[108:109], v[148:149]
	v_pk_fma_f32 v[148:149], v[146:147], v[110:111], v[148:149]
	v_cvt_pk_f32_fp8_e32 v[140:141], v46
	v_cvt_pk_f32_fp8_sdwa v[142:143], v46 src0_sel:WORD_1
	v_cvt_pk_f32_fp8_e32 v[144:145], v47
	v_cvt_pk_f32_fp8_sdwa v[146:147], v47 src0_sel:WORD_1
	v_pk_fma_f32 v[148:149], v[140:141], v[112:113], v[148:149]
	v_pk_fma_f32 v[148:149], v[142:143], v[114:115], v[148:149]
	v_pk_fma_f32 v[148:149], v[144:145], v[116:117], v[148:149]
	v_pk_fma_f32 v[148:149], v[146:147], v[118:119], v[148:149]
	v_add_f32_e32 v167, v148, v149
	v_lshl_add_u32 v4, v81, 7, v0
	global_load_dwordx4 v[44:47], v4, s[40:41]
	s_waitcnt vmcnt(15)
	v_cvt_pk_f32_fp8_e32 v[140:141], v48
	v_cvt_pk_f32_fp8_sdwa v[142:143], v48 src0_sel:WORD_1
	v_cvt_pk_f32_fp8_e32 v[144:145], v49
	v_cvt_pk_f32_fp8_sdwa v[146:147], v49 src0_sel:WORD_1
	v_pk_mul_f32 v[148:149], v[140:141], v[104:105]
	v_pk_fma_f32 v[148:149], v[142:143], v[106:107], v[148:149]
	v_pk_fma_f32 v[148:149], v[144:145], v[108:109], v[148:149]
	v_pk_fma_f32 v[148:149], v[146:147], v[110:111], v[148:149]
	v_cvt_pk_f32_fp8_e32 v[140:141], v50
	v_cvt_pk_f32_fp8_sdwa v[142:143], v50 src0_sel:WORD_1
	v_cvt_pk_f32_fp8_e32 v[144:145], v51
	v_cvt_pk_f32_fp8_sdwa v[146:147], v51 src0_sel:WORD_1
	v_pk_fma_f32 v[148:149], v[140:141], v[112:113], v[148:149]
	v_pk_fma_f32 v[148:149], v[142:143], v[114:115], v[148:149]
	v_pk_fma_f32 v[148:149], v[144:145], v[116:117], v[148:149]
	v_pk_fma_f32 v[148:149], v[146:147], v[118:119], v[148:149]
	v_add_f32_e32 v168, v148, v149
	v_lshl_add_u32 v3, v82, 7, v0
	global_load_dwordx4 v[48:51], v3, s[40:41]
	s_waitcnt vmcnt(15)
; #define FP8_LO(w) __builtin_amdgcn_cvt_pk_f32_fp8((int)(w), false)
; #define FP8_HI(w) __builtin_amdgcn_cvt_pk_f32_fp8((int)(w), true)
; DI float dot16p(const u32x4 xa, const u32x4 xb, const u32x4 w) {
;     const f32x2 a0 = FP8_LO(w.x), a1 = FP8_HI(w.x), a2 = FP8_LO(w.y), a3 = FP8_HI(w.y), a4 = FP8_LO(w.z), a5 = FP8_HI(w.z), a6 = FP8_LO(w.w), a7 = FP8_HI(w.w);
;     return (bflo(xa.x) * a0.x + bfhi(xa.x) * a0.y + bflo(xa.y) * a1.x + bfhi(xa.y) * a1.y) + (bflo(xa.z) * a2.x + bfhi(xa.z) * a2.y + bflo(xa.w) * a3.x + bfhi(xa.w) * a3.y)
;          + (bflo(xb.x) * a4.x + bfhi(xb.x) * a4.y + bflo(xb.y) * a5.x + bfhi(xb.y) * a5.y) + (bflo(xb.z) * a6.x + bfhi(xb.z) * a6.y + bflo(xb.w) * a7.x + bfhi(xb.w) * a7.y);
	v_cvt_pk_f32_fp8_e32 v[140:141], v52
	v_cvt_pk_f32_fp8_sdwa v[142:143], v52 src0_sel:WORD_1
	v_cvt_pk_f32_fp8_e32 v[144:145], v53
	v_cvt_pk_f32_fp8_sdwa v[146:147], v53 src0_sel:WORD_1
	v_pk_mul_f32 v[148:149], v[140:141], v[104:105]
	v_pk_fma_f32 v[148:149], v[142:143], v[106:107], v[148:149]
	v_pk_fma_f32 v[148:149], v[144:145], v[108:109], v[148:149]
	v_pk_fma_f32 v[148:149], v[146:147], v[110:111], v[148:149]
	v_cvt_pk_f32_fp8_e32 v[140:141], v54
	v_cvt_pk_f32_fp8_sdwa v[142:143], v54 src0_sel:WORD_1
	v_cvt_pk_f32_fp8_e32 v[144:145], v55
	v_cvt_pk_f32_fp8_sdwa v[146:147], v55 src0_sel:WORD_1
	v_pk_fma_f32 v[148:149], v[140:141], v[112:113], v[148:149]
	v_pk_fma_f32 v[148:149], v[142:143], v[114:115], v[148:149]
	v_pk_fma_f32 v[148:149], v[144:145], v[116:117], v[148:149]
	v_pk_fma_f32 v[148:149], v[146:147], v[118:119], v[148:149]
	v_add_f32_e32 v169, v148, v149
	v_lshl_add_u32 v4, v83, 7, v0
	global_load_dwordx4 v[52:55], v4, s[40:41]
	s_waitcnt vmcnt(15)
	v_cvt_pk_f32_fp8_e32 v[140:141], v56
	v_cvt_pk_f32_fp8_sdwa v[142:143], v56 src0_sel:WORD_1
	v_cvt_pk_f32_fp8_e32 v[144:145], v57
	v_cvt_pk_f32_fp8_sdwa v[146:147], v57 src0_sel:WORD_1
	v_pk_mul_f32 v[148:149], v[140:141], v[104:105]
	v_pk_fma_f32 v[148:149], v[142:143], v[106:107], v[148:149]
	v_pk_fma_f32 v[148:149], v[144:145], v[108:109], v[148:149]
	v_pk_fma_f32 v[148:149], v[146:147], v[110:111], v[148:149]
	v_cvt_pk_f32_fp8_e32 v[140:141], v58
	v_cvt_pk_f32_fp8_sdwa v[142:143], v58 src0_sel:WORD_1
	v_cvt_pk_f32_fp8_e32 v[144:145], v59
	v_cvt_pk_f32_fp8_sdwa v[146:147], v59 src0_sel:WORD_1
	v_pk_fma_f32 v[148:149], v[140:141], v[112:113], v[148:149]
	v_pk_fma_f32 v[148:149], v[142:143], v[114:115], v[148:149]
	v_pk_fma_f32 v[148:149], v[144:145], v[116:117], v[148:149]
	v_pk_fma_f32 v[148:149], v[146:147], v[118:119], v[148:149]
	v_add_f32_e32 v170, v148, v149
	v_lshl_add_u32 v3, v84, 7, v0
	global_load_dwordx4 v[56:59], v3, s[40:41]
	s_waitcnt vmcnt(15)
	v_cvt_pk_f32_fp8_e32 v[140:141], v60
	v_cvt_pk_f32_fp8_sdwa v[142:143], v60 src0_sel:WORD_1
	v_cvt_pk_f32_fp8_e32 v[144:145], v61
	v_cvt_pk_f32_fp8_sdwa v[146:147], v61 src0_sel:WORD_1
	v_pk_mul_f32 v[148:149], v[140:141], v[104:105]
	v_pk_fma_f32 v[148:149], v[142:143], v[106:107], v[148:149]
	v_pk_fma_f32 v[148:149], v[144:145], v[108:109], v[148:149]
	v_pk_fma_f32 v[148:149], v[146:147], v[110:111], v[148:149]
	v_cvt_pk_f32_fp8_e32 v[140:141], v62
	v_cvt_pk_f32_fp8_sdwa v[142:143], v62 src0_sel:WORD_1
	v_cvt_pk_f32_fp8_e32 v[144:145], v63
	v_cvt_pk_f32_fp8_sdwa v[146:147], v63 src0_sel:WORD_1
	v_pk_fma_f32 v[148:149], v[140:141], v[112:113], v[148:149]
	v_pk_fma_f32 v[148:149], v[142:143], v[114:115], v[148:149]
	v_pk_fma_f32 v[148:149], v[144:145], v[116:117], v[148:149]
	v_pk_fma_f32 v[148:149], v[146:147], v[118:119], v[148:149]
	v_add_f32_e32 v171, v148, v149
	v_lshl_add_u32 v4, v85, 7, v0
	global_load_dwordx4 v[60:63], v4, s[40:41]
	s_waitcnt vmcnt(15)
	v_cvt_pk_f32_fp8_e32 v[140:141], v64
	v_cvt_pk_f32_fp8_sdwa v[142:143], v64 src0_sel:WORD_1
	v_cvt_pk_f32_fp8_e32 v[144:145], v65
	v_cvt_pk_f32_fp8_sdwa v[146:147], v65 src0_sel:WORD_1
	v_pk_mul_f32 v[148:149], v[140:141], v[104:105]
	v_pk_fma_f32 v[148:149], v[142:143], v[106:107], v[148:149]
	v_pk_fma_f32 v[148:149], v[144:145], v[108:109], v[148:149]
	v_pk_fma_f32 v[148:149], v[146:147], v[110:111], v[148:149]
	v_cvt_pk_f32_fp8_e32 v[140:141], v66
	v_cvt_pk_f32_fp8_sdwa v[142:143], v66 src0_sel:WORD_1
	v_cvt_pk_f32_fp8_e32 v[144:145], v67
	v_cvt_pk_f32_fp8_sdwa v[146:147], v67 src0_sel:WORD_1
	v_pk_fma_f32 v[148:149], v[140:141], v[112:113], v[148:149]
	v_pk_fma_f32 v[148:149], v[142:143], v[114:115], v[148:149]
	v_pk_fma_f32 v[148:149], v[144:145], v[116:117], v[148:149]
	v_pk_fma_f32 v[148:149], v[146:147], v[118:119], v[148:149]
	v_add_f32_e32 v172, v148, v149
	v_lshl_add_u32 v3, v86, 7, v0
	global_load_dwordx4 v[64:67], v3, s[40:41]
	s_waitcnt vmcnt(15)
; DI float dots4h(const u32x4 xa, const u32x4 xb, const u32x4 b0, const u32x4 b1, const u32x4 b2, const u32x4 b3, int lane) {
;     const float d0 = dot16p(xa, xb, b0), d1 = dot16p(xa, xb, b1); __builtin_amdgcn_sched_barrier(0);
;     const float d2 = dot16p(xa, xb, b2), d3 = dot16p(xa, xb, b3); __builtin_amdgcn_sched_barrier(0);
;     const bool p1 = lane & 1, p2 = lane & 2;
;     const float b0s = (p1 ? d1 : d0) + __shfl_xor(p1 ? d0 : d1, 1);
;     const float b1s = (p1 ? d3 : d2) + __shfl_xor(p1 ? d2 : d3, 1);
;     float cs = (p2 ? b1s : b0s) + __shfl_xor(p2 ? b0s : b1s, 2);
;     cs += __shfl_xor(cs, 4); cs += __shfl_xor(cs, 8); cs += __shfl_xor(cs, 16); cs += __shfl_xor(cs, 32);
;     return cs;
; DI void phase_peer_u(const Args& a, int layer, int ci) {
;     ...
;             if (ci == 0) { PD[(size_t)m * 128 + lane] = rA; PD[(size_t)m * 128 + 64 + lane] = rB; }
	v_cvt_pk_f32_fp8_e32 v[140:141], v68
	v_cvt_pk_f32_fp8_sdwa v[142:143], v68 src0_sel:WORD_1
	v_cvt_pk_f32_fp8_e32 v[144:145], v69
	v_cvt_pk_f32_fp8_sdwa v[146:147], v69 src0_sel:WORD_1
	v_pk_mul_f32 v[148:149], v[140:141], v[104:105]
	v_pk_fma_f32 v[148:149], v[142:143], v[106:107], v[148:149]
	v_pk_fma_f32 v[148:149], v[144:145], v[108:109], v[148:149]
	v_pk_fma_f32 v[148:149], v[146:147], v[110:111], v[148:149]
	v_cvt_pk_f32_fp8_e32 v[140:141], v70
	v_cvt_pk_f32_fp8_sdwa v[142:143], v70 src0_sel:WORD_1
	v_cvt_pk_f32_fp8_e32 v[144:145], v71
	v_cvt_pk_f32_fp8_sdwa v[146:147], v71 src0_sel:WORD_1
	v_pk_fma_f32 v[148:149], v[140:141], v[112:113], v[148:149]
	v_pk_fma_f32 v[148:149], v[142:143], v[114:115], v[148:149]
	v_pk_fma_f32 v[148:149], v[144:145], v[116:117], v[148:149]
	v_pk_fma_f32 v[148:149], v[146:147], v[118:119], v[148:149]
	v_add_f32_e32 v173, v148, v149
	v_lshl_add_u32 v4, v87, 7, v0
	global_load_dwordx4 v[68:71], v4, s[40:41]
	v_cndmask_b32_e64 v152, v156, v157, s[34:35]
	v_cndmask_b32_e64 v174, v157, v156, s[34:35]
	v_cndmask_b32_e64 v153, v158, v159, s[34:35]
	v_cndmask_b32_e64 v175, v159, v158, s[34:35]
	v_cndmask_b32_e64 v154, v160, v161, s[34:35]
	v_cndmask_b32_e64 v176, v161, v160, s[34:35]
	v_cndmask_b32_e64 v155, v162, v163, s[34:35]
	v_cndmask_b32_e64 v177, v163, v162, s[34:35]
	v_add_f32_dpp v156, v174, v152 quad_perm:[1,0,3,2] row_mask:0xf bank_mask:0xf
	v_add_f32_dpp v157, v175, v153 quad_perm:[1,0,3,2] row_mask:0xf bank_mask:0xf
	v_add_f32_dpp v158, v176, v154 quad_perm:[1,0,3,2] row_mask:0xf bank_mask:0xf
	v_add_f32_dpp v159, v177, v155 quad_perm:[1,0,3,2] row_mask:0xf bank_mask:0xf
	v_cndmask_b32_e64 v152, v166, v167, s[34:35]
	v_cndmask_b32_e64 v174, v167, v166, s[34:35]
	v_cndmask_b32_e64 v153, v168, v169, s[34:35]
	v_cndmask_b32_e64 v175, v169, v168, s[34:35]
	v_cndmask_b32_e64 v154, v170, v171, s[34:35]
	v_cndmask_b32_e64 v176, v171, v170, s[34:35]
	v_cndmask_b32_e64 v155, v172, v173, s[34:35]
	v_cndmask_b32_e64 v177, v173, v172, s[34:35]
	v_add_f32_dpp v160, v174, v152 quad_perm:[1,0,3,2] row_mask:0xf bank_mask:0xf
	v_add_f32_dpp v161, v175, v153 quad_perm:[1,0,3,2] row_mask:0xf bank_mask:0xf
	v_add_f32_dpp v162, v176, v154 quad_perm:[1,0,3,2] row_mask:0xf bank_mask:0xf
	v_add_f32_dpp v163, v177, v155 quad_perm:[1,0,3,2] row_mask:0xf bank_mask:0xf
	v_cndmask_b32_e64 v152, v156, v157, s[48:49]
	v_cndmask_b32_e64 v174, v157, v156, s[48:49]
	v_cndmask_b32_e64 v153, v158, v159, s[48:49]
	v_cndmask_b32_e64 v175, v159, v158, s[48:49]
	v_cndmask_b32_e64 v154, v160, v161, s[48:49]
	v_cndmask_b32_e64 v176, v161, v160, s[48:49]
	v_cndmask_b32_e64 v155, v162, v163, s[48:49]
	v_cndmask_b32_e64 v177, v163, v162, s[48:49]
	v_add_f32_dpp v156, v174, v152 quad_perm:[2,3,0,1] row_mask:0xf bank_mask:0xf
	v_add_f32_dpp v157, v175, v153 quad_perm:[2,3,0,1] row_mask:0xf bank_mask:0xf
	v_add_f32_dpp v158, v176, v154 quad_perm:[2,3,0,1] row_mask:0xf bank_mask:0xf
	v_add_f32_dpp v159, v177, v155 quad_perm:[2,3,0,1] row_mask:0xf bank_mask:0xf
	v_mov_b64_e32 v[216:217], v[218:219]
	v_mov_b64_e32 v[218:219], v[220:221]
	v_mov_b64_e32 v[220:221], v[222:223]
	v_mov_b64_e32 v[222:223], v[224:225]
	v_mov_b64_e32 v[224:225], v[226:227]
	v_mov_b64_e32 v[226:227], v[232:233]
	v_mov_b64_e32 v[232:233], v[234:235]
	v_cndmask_b32_e64 v152, v156, v157, s[50:51]
	v_cndmask_b32_e64 v174, v157, v156, s[50:51]
	v_cndmask_b32_e64 v153, v158, v159, s[50:51]
	v_cndmask_b32_e64 v175, v159, v158, s[50:51]
	v_add_f32_dpp v234, v174, v152 row_shl:4 row_mask:0xf bank_mask:0x5
	v_add_f32_dpp v234, v174, v152 row_shr:4 row_mask:0xf bank_mask:0xa
	v_add_f32_dpp v235, v175, v153 row_shl:4 row_mask:0xf bank_mask:0x5
	v_add_f32_dpp v235, v175, v153 row_shr:4 row_mask:0xf bank_mask:0xa
	s_cmp_eq_u32 s47, 7
	s_cbranch_scc0 .Lpu_b1_nost
	s_bfe_u32 s45, s0, 0x40003
	s_lshl_b32 s45, s45, 20
	s_add_u32 s45, s45, s8
	s_lshr_b32 s46, s0, 7
	s_add_u32 s46, s46, s9
	s_lshl_b32 s46, s46, 24
	s_add_u32 s45, s45, s46
	s_add_u32 s45, s45, 0x20000000
	s_add_u32 s42, s98, s45
	s_addc_u32 s43, s99, 0
	s_cmp_ge_u32 s0, 0x80
	s_cbranch_scc0 .Lpu_b1_noadd
	v_pk_add_f32 v[216:217], v[216:217], v[180:181]
	v_pk_add_f32 v[218:219], v[218:219], v[182:183]
	v_pk_add_f32 v[220:221], v[220:221], v[192:193]
	v_pk_add_f32 v[222:223], v[222:223], v[194:195]
	v_pk_add_f32 v[224:225], v[224:225], v[200:201]
	v_pk_add_f32 v[226:227], v[226:227], v[202:203]
	v_pk_add_f32 v[232:233], v[232:233], v[244:245]
	v_pk_add_f32 v[234:235], v[234:235], v[246:247]

; DI void phase_peer_u(const Args& a, int layer, int ci) {
;     ...
;             float glA = 0.f, glB = 0.f, pdA = 0.f, pdB = 0.f, rstdu = 0.f;
;             if (ci == 1) {
;                 glA = GATE[(size_t)m * 128 + lane] * GSUM[(size_t)m * 8 + (lane >> 4)] * (1.f / V_SCALE);
;                 glB = GATE[(size_t)m * 128 + 64 + lane] * GSUM[(size_t)m * 8 + 4 + (lane >> 4)] * (1.f / V_SCALE);
;                 pdA = PD[(size_t)m * 128 + lane]; pdB = PD[(size_t)m * 128 + 64 + lane];
;                 rstdu = __builtin_bit_cast(float, __builtin_amdgcn_readfirstlane(__builtin_bit_cast(int, rsqrtf(wave_sum(lane < 32 ? ((const float*)(ws + WS_RSS))[((size_t)layer * M + m) * 32 + lane] : 0.f) * (1.f / D) + 1e-6f) * (1.f / U_SCALE))));
;             }
.Lpuc_entry:
	v_readlane_b32 s1, v252, 0
	v_readlane_b32 s19, v255, 12
	v_lshrrev_b32_e32 v5, 6, v185
	v_and_b32_e32 v6, 63, v185
	v_lshlrev_b32_e32 v0, 2, v6
	v_and_b32_e32 v1, 31, v6
	v_lshlrev_b32_e32 v1, 2, v1
	v_lshrrev_b32_e32 v3, 5, v6
	v_bfe_u32 v4, v6, 1, 1
	v_lshl_or_b32 v3, v3, 1, v4
	v_bfe_u32 v7, v6, 2, 3
	v_and_b32_e32 v4, 1, v6
	v_lshl_or_b32 v2, v3, 4, v7
	v_lshl_or_b32 v2, v4, 3, v2
	v_lshlrev_b32_e32 v2, 2, v2
	v_lshlrev_b32_e32 v3, 2, v3
	v_readfirstlane_b32 s44, v5
	s_lshl_b32 s45, s1, 3
	s_add_u32 s45, s45, s44
	s_lshl_b32 s46, s45, 13
	s_add_u32 s46, s46, 0x20000000
	s_add_u32 s38, s98, s46
	s_addc_u32 s39, s99, 0
	s_lshl_b32 s46, s45, 13
	s_add_u32 s46, s46, 0x7000000
	s_add_u32 s42, s98, s46
	s_addc_u32 s43, s99, 0
	s_mov_b64 s[16:17], s[42:43]
	s_lshl_b32 s46, s19, 22
	s_lshl_b32 s47, s45, 11
	s_add_u32 s46, s46, s47
	s_add_u32 s46, s46, 0xd800000
	s_add_u32 s40, s98, s46
	s_addc_u32 s41, s99, 0
	s_lshl_b32 s46, s45, 9
	s_add_u32 s46, s46, 0x5e00000
	s_add_u32 s24, s98, s46
	s_addc_u32 s25, s99, 0
	s_mov_b32 s101, 0x39800000
	s_mov_b32 s19, 0x3d372713
	s_mov_b32 s100, 0x200
	s_mov_b32 s0, 0
	s_add_u32 s22, s38, 0x1000000
	s_addc_u32 s23, s39, 0
	global_load_dword v8, v0, s[22:23]
	global_load_dword v9, v0, s[22:23] offset:256
	s_add_u32 s22, s22, 0x2000000
	s_addc_u32 s23, s23, 0
	global_load_dword v10, v0, s[22:23]
	global_load_dword v11, v0, s[22:23] offset:256
	s_add_u32 s22, s22, 0x2000000
	s_addc_u32 s23, s23, 0
	global_load_dword v12, v0, s[22:23]
	global_load_dword v13, v0, s[22:23] offset:256
	s_add_u32 s22, s22, 0x2000000
	s_addc_u32 s23, s23, 0
	global_load_dword v14, v0, s[22:23]
	global_load_dword v15, v0, s[22:23] offset:256
	s_add_u32 s22, s22, 0x2000000
	s_addc_u32 s23, s23, 0
	global_load_dword v16, v0, s[22:23]
	global_load_dword v17, v0, s[22:23] offset:256
	s_add_u32 s22, s22, 0x2000000
	s_addc_u32 s23, s23, 0
	global_load_dword v18, v0, s[22:23]
	global_load_dword v19, v0, s[22:23] offset:256
	s_add_u32 s22, s22, 0x2000000
	s_addc_u32 s23, s23, 0
	global_load_dword v20, v0, s[22:23]
	global_load_dword v21, v0, s[22:23] offset:256
	s_add_u32 s22, s22, 0x2000000
	s_addc_u32 s23, s23, 0
	global_load_dword v22, v0, s[22:23]
	global_load_dword v23, v0, s[22:23] offset:256
	global_load_dword v40, v1, s[40:41]
	global_load_dword v41, v2, s[42:43]
	global_load_dword v42, v2, s[42:43] offset:256
	global_load_dword v43, v3, s[24:25]
	global_load_dword v44, v3, s[24:25] offset:16
.Lpuc_loop:
	s_add_u32 s38, s38, s100
	s_addc_u32 s39, s39, 0
	s_lshr_b32 s44, s100, 2
	s_add_u32 s40, s40, s44
	s_addc_u32 s41, s41, 0
	s_lshr_b32 s44, s100, 4
	s_add_u32 s24, s24, s44
	s_addc_u32 s25, s25, 0
	s_add_u32 s42, s42, s100
	s_addc_u32 s43, s43, 0
	s_add_u32 s22, s38, 0x1000000
	s_addc_u32 s23, s39, 0
	global_load_dword v56, v0, s[22:23]
	global_load_dword v57, v0, s[22:23] offset:256
	s_add_u32 s22, s22, 0x2000000
	s_addc_u32 s23, s23, 0
	global_load_dword v58, v0, s[22:23]
	global_load_dword v59, v0, s[22:23] offset:256
	s_add_u32 s22, s22, 0x2000000
	s_addc_u32 s23, s23, 0
	global_load_dword v60, v0, s[22:23]
	global_load_dword v61, v0, s[22:23] offset:256
	s_add_u32 s22, s22, 0x2000000
	s_addc_u32 s23, s23, 0
	global_load_dword v62, v0, s[22:23]
	global_load_dword v63, v0, s[22:23] offset:256
	s_add_u32 s22, s22, 0x2000000
	s_addc_u32 s23, s23, 0
	global_load_dword v64, v0, s[22:23]
	global_load_dword v65, v0, s[22:23] offset:256
	s_add_u32 s22, s22, 0x2000000
	s_addc_u32 s23, s23, 0
	global_load_dword v66, v0, s[22:23]
	global_load_dword v67, v0, s[22:23] offset:256
	s_add_u32 s22, s22, 0x2000000
	s_addc_u32 s23, s23, 0
	global_load_dword v68, v0, s[22:23]
	global_load_dword v69, v0, s[22:23] offset:256
	s_add_u32 s22, s22, 0x2000000
	s_addc_u32 s23, s23, 0
	global_load_dword v70, v0, s[22:23]
	global_load_dword v71, v0, s[22:23] offset:256
	global_load_dword v88, v1, s[40:41]
	global_load_dword v89, v2, s[42:43]
	global_load_dword v90, v2, s[42:43] offset:256
	global_load_dword v91, v3, s[24:25]
	global_load_dword v92, v3, s[24:25] offset:16
	s_waitcnt vmcnt(21)
; DI float gelu_tanh(float x) {
;     const float y = 0.7978845608028654f * (x + 0.044715f * x * x * x);
;     const float t = __expf(2.f * y);
;     const float th = 1.f - 2.f / (t + 1.f);
;     return 0.5f * x * (1.f + th);
; }
; DI void phase_peer_u(const Args& a, int layer, int ci) {
;     ...
;             if (ci == 1) {
;                 glA = GATE[(size_t)m * 128 + lane] * GSUM[(size_t)m * 8 + (lane >> 4)] * (1.f / V_SCALE);
;                 glB = GATE[(size_t)m * 128 + 64 + lane] * GSUM[(size_t)m * 8 + 4 + (lane >> 4)] * (1.f / V_SCALE);
;                 pdA = PD[(size_t)m * 128 + lane]; pdB = PD[(size_t)m * 128 + 64 + lane];
;                 rstdu = __builtin_bit_cast(float, __builtin_amdgcn_readfirstlane(__builtin_bit_cast(int, rsqrtf(wave_sum(lane < 32 ? ((const float*)(ws + WS_RSS))[((size_t)layer * M + m) * 32 + lane] : 0.f) * (1.f / D) + 1e-6f) * (1.f / U_SCALE))));
;             }
;             float rA = 0.f, rB = 0.f;
; #pragma unroll 1
;             for (int g8 = 0; g8 < 16; ++g8) {
;                 u32x4 nxt[8];
;                 if (g8 < 15) gat_loadhu(U, idA, idB, g8 + 1, lo16, nxt); else gat_loadhu(U, idAn, idBn, 0, lo16, nxt);
;                 const float c0 = dots4h(xa, xb, cur[0], cur[1], cur[2], cur[3], lane);
;                 const float c1 = dots4h(xa, xb, cur[4], cur[5], cur[6], cur[7], lane);
;                 const int q4 = (g8 & 7) * 2;
;                 const float cv = (lane >> 2) == q4 ? c0 : c1;
;                 const bool mine = (lane >> 3) == (g8 & 7);
;                 if (ci == 0) { if (g8 < 8) rA = mine ? cv : rA; else rB = mine ? cv : rB; }
;                 else { if (g8 < 8) rA = mine ? gelu_tanh((cv + pdA) * rstdu) * glA : rA; else rB = mine ? gelu_tanh((cv + pdB) * rstdu) * glB : rB; }
; #pragma unroll
;                 for (int j = 0; j < 8; ++j) cur[j] = nxt[j];
;             }
;             if (ci == 0) { PD[(size_t)m * 128 + lane] = rA; PD[(size_t)m * 128 + 64 + lane] = rB; }
;             else { GATE[(size_t)m * 128 + lane] = rA; GATE[(size_t)m * 128 + 64 + lane] = rB; }
	v_add_f32_e32 v104, v8, v10
	v_add_f32_e32 v104, v104, v12
	v_add_f32_e32 v104, v104, v14
	v_add_f32_e32 v104, v104, v16
	v_add_f32_e32 v104, v104, v18
	v_add_f32_e32 v104, v104, v20
	v_add_f32_e32 v104, v104, v22
	v_add_f32_e32 v105, v9, v11
	v_add_f32_e32 v105, v105, v13
	v_add_f32_e32 v105, v105, v15
	v_add_f32_e32 v105, v105, v17
	v_add_f32_e32 v105, v105, v19
	v_add_f32_e32 v105, v105, v21
	v_add_f32_e32 v105, v105, v23
	v_mov_b32_e32 v106, v40
	s_nop 1
	v_add_f32_dpp v106, v106, v106 quad_perm:[1,0,3,2] row_mask:0xf bank_mask:0xf
	s_nop 1
	v_add_f32_dpp v106, v106, v106 quad_perm:[2,3,0,1] row_mask:0xf bank_mask:0xf
	s_nop 1
	v_add_f32_dpp v106, v106, v106 row_half_mirror row_mask:0xf bank_mask:0xf
	s_nop 1
	v_add_f32_dpp v106, v106, v106 row_mirror row_mask:0xf bank_mask:0xf
	s_nop 1
	v_readlane_b32 s44, v106, 0
	v_readlane_b32 s45, v106, 16
	v_readlane_b32 s46, v106, 32
	v_readlane_b32 s47, v106, 48
	s_nop 1
	v_mov_b32_e32 v107, s44
	v_add_f32_e32 v107, s45, v107
	v_add_f32_e32 v107, s46, v107
	v_add_f32_e32 v107, s47, v107
	v_fma_f32 v107, v107, s101, v190
	v_rsq_f32_e32 v107, v107
	s_nop 0
	v_mul_f32_e32 v107, 0x3b000000, v107
	v_mul_f32_e32 v108, 0x3c800000, v43
	v_mul_f32_e32 v109, 0x3c800000, v44
	v_mul_f32_e32 v108, v108, v41
	v_mul_f32_e32 v109, v109, v42
	v_mul_f32_e32 v104, v104, v107
	v_mul_f32_e32 v110, v104, v104
	v_mul_f32_e32 v110, v110, v104
	v_fma_f32 v110, v110, s19, v104
	v_mul_f32_e32 v110, 0x40135761, v110
	v_exp_f32_e32 v110, v110
	s_nop 0
	v_add_f32_e32 v110, 1.0, v110
	v_rcp_f32_e32 v110, v110
	s_nop 0
	v_fma_f32 v111, -v104, v110, v104
	v_mul_f32_e32 v111, v111, v108
	v_mul_f32_e32 v105, v105, v107
	v_mul_f32_e32 v112, v105, v105
	v_mul_f32_e32 v112, v112, v105
	v_fma_f32 v112, v112, s19, v105
	v_mul_f32_e32 v112, 0x40135761, v112
	v_exp_f32_e32 v112, v112
	s_nop 0
	v_add_f32_e32 v112, 1.0, v112
	v_rcp_f32_e32 v112, v112
	s_nop 0
	v_fma_f32 v113, -v105, v112, v105
	v_mul_f32_e32 v113, v113, v109
	global_store_dword v2, v111, s[16:17]
	global_store_dword v2, v113, s[16:17] offset:256
	s_add_u32 s16, s16, 0x200
	s_addc_u32 s17, s17, 0
	s_cmp_eq_u32 s0, 7
	s_cselect_b32 s100, 0, s100
	s_add_u32 s38, s38, s100
	s_addc_u32 s39, s39, 0
	s_lshr_b32 s44, s100, 2
	s_add_u32 s40, s40, s44
	s_addc_u32 s41, s41, 0
	s_lshr_b32 s44, s100, 4
	s_add_u32 s24, s24, s44
	s_addc_u32 s25, s25, 0
	s_add_u32 s42, s42, s100
	s_addc_u32 s43, s43, 0
	s_add_u32 s22, s38, 0x1000000
	s_addc_u32 s23, s39, 0
	global_load_dword v8, v0, s[22:23]
	global_load_dword v9, v0, s[22:23] offset:256
	s_add_u32 s22, s22, 0x2000000
	s_addc_u32 s23, s23, 0
	global_load_dword v10, v0, s[22:23]
	global_load_dword v11, v0, s[22:23] offset:256
	s_add_u32 s22, s22, 0x2000000
	s_addc_u32 s23, s23, 0
	global_load_dword v12, v0, s[22:23]
	global_load_dword v13, v0, s[22:23] offset:256
	s_add_u32 s22, s22, 0x2000000
	s_addc_u32 s23, s23, 0
	global_load_dword v14, v0, s[22:23]
	global_load_dword v15, v0, s[22:23] offset:256
	s_add_u32 s22, s22, 0x2000000
	s_addc_u32 s23, s23, 0
	global_load_dword v16, v0, s[22:23]
	global_load_dword v17, v0, s[22:23] offset:256
	s_add_u32 s22, s22, 0x2000000
	s_addc_u32 s23, s23, 0
	global_load_dword v18, v0, s[22:23]
	global_load_dword v19, v0, s[22:23] offset:256
	s_add_u32 s22, s22, 0x2000000
	s_addc_u32 s23, s23, 0
	global_load_dword v20, v0, s[22:23]
	global_load_dword v21, v0, s[22:23] offset:256
	s_add_u32 s22, s22, 0x2000000
	s_addc_u32 s23, s23, 0
	global_load_dword v22, v0, s[22:23]
	global_load_dword v23, v0, s[22:23] offset:256
	global_load_dword v40, v1, s[40:41]
	global_load_dword v41, v2, s[42:43]
	global_load_dword v42, v2, s[42:43] offset:256
	global_load_dword v43, v3, s[24:25]
	global_load_dword v44, v3, s[24:25] offset:16
	s_waitcnt vmcnt(21)
	v_add_f32_e32 v104, v56, v58
	v_add_f32_e32 v104, v104, v60
	v_add_f32_e32 v104, v104, v62
	v_add_f32_e32 v104, v104, v64
	v_add_f32_e32 v104, v104, v66
	v_add_f32_e32 v104, v104, v68
	v_add_f32_e32 v104, v104, v70
	v_add_f32_e32 v105, v57, v59
	v_add_f32_e32 v105, v105, v61
	v_add_f32_e32 v105, v105, v63
	v_add_f32_e32 v105, v105, v65
	v_add_f32_e32 v105, v105, v67
	v_add_f32_e32 v105, v105, v69
	v_add_f32_e32 v105, v105, v71
	v_mov_b32_e32 v106, v88
	s_nop 1
	v_add_f32_dpp v106, v106, v106 quad_perm:[1,0,3,2] row_mask:0xf bank_mask:0xf
	s_nop 1
	v_add_f32_dpp v106, v106, v106 quad_perm:[2,3,0,1] row_mask:0xf bank_mask:0xf
	s_nop 1
	v_add_f32_dpp v106, v106, v106 row_half_mirror row_mask:0xf bank_mask:0xf
	s_nop 1
	v_add_f32_dpp v106, v106, v106 row_mirror row_mask:0xf bank_mask:0xf
	s_nop 1
	v_readlane_b32 s44, v106, 0
	v_readlane_b32 s45, v106, 16
	v_readlane_b32 s46, v106, 32
	v_readlane_b32 s47, v106, 48
	s_nop 1
	v_mov_b32_e32 v107, s44
	v_add_f32_e32 v107, s45, v107
	v_add_f32_e32 v107, s46, v107
	v_add_f32_e32 v107, s47, v107
	v_fma_f32 v107, v107, s101, v190
	v_rsq_f32_e32 v107, v107
	s_nop 0
	v_mul_f32_e32 v107, 0x3b000000, v107
	v_mul_f32_e32 v108, 0x3c800000, v91
	v_mul_f32_e32 v109, 0x3c800000, v92
	v_mul_f32_e32 v108, v108, v89
	v_mul_f32_e32 v109, v109, v90
	v_mul_f32_e32 v104, v104, v107
	v_mul_f32_e32 v110, v104, v104
	v_mul_f32_e32 v110, v110, v104
	v_fma_f32 v110, v110, s19, v104
	v_mul_f32_e32 v110, 0x40135761, v110
	v_exp_f32_e32 v110, v110
	s_nop 0
	v_add_f32_e32 v110, 1.0, v110
	v_rcp_f32_e32 v110, v110
	s_nop 0
	v_fma_f32 v111, -v104, v110, v104
	v_mul_f32_e32 v111, v111, v108
	v_mul_f32_e32 v105, v105, v107
	v_mul_f32_e32 v112, v105, v105
	v_mul_f32_e32 v112, v112, v105
	v_fma_f32 v112, v112, s19, v105
	v_mul_f32_e32 v112, 0x40135761, v112
	v_exp_f32_e32 v112, v112
	s_nop 0
	v_add_f32_e32 v112, 1.0, v112
	v_rcp_f32_e32 v112, v112
	s_nop 0
	v_fma_f32 v113, -v105, v112, v105
	v_mul_f32_e32 v113, v113, v109
	global_store_dword v2, v111, s[16:17]
	global_store_dword v2, v113, s[16:17] offset:256
	s_add_u32 s16, s16, 0x200
	s_addc_u32 s17, s17, 0
	s_add_u32 s0, s0, 1
	s_cmp_lt_u32 s0, 8
	s_cbranch_scc1 .Lpuc_loop
	s_waitcnt vmcnt(0)
	s_branch .LBB0_495
